# physical XCD affinity: workgroups renumber themselves by (XCC id, arrival rank) after phase 0 so the static tile/unit order's XCD is the real one; XCD-local barriers at the 9 seams whose data stays in
# speedup vs baseline: 1.0220x; 1.0220x over previous
.LBB0_4:
	s_or_b64 exec, exec, s[0:1]
	s_waitcnt lgkmcnt(0)
	s_barrier
	s_add_u32 s28, s38, 0xc0000
	s_getreg_b32 s26, hwreg(HW_REG_XCC_ID, 0, 4)
	s_addc_u32 s29, s39, 0
	s_and_b32 s31, s26, 15
	s_mov_b64 s[0:1], exec
	v_readlane_b32 s16, v254, 4
	v_readlane_b32 s17, v254, 5
	s_and_b64 s[16:17], s[0:1], s[16:17]
	s_mov_b64 exec, s[16:17]
	s_cbranch_execz .LBB0_7
	s_mov_b64 s[16:17], exec
	v_mbcnt_lo_u32_b32 v1, s16, 0
	v_mbcnt_hi_u32_b32 v1, s17, v1
	v_cmp_eq_u32_e32 vcc, 0, v1
	s_and_b64 s[34:35], exec, vcc
	s_mov_b64 exec, s[34:35]
	s_cbranch_execz .LBB0_7
	s_and_b32 s26, s26, 8
	s_add_u32 s26, s28, s26
	s_addc_u32 s27, s29, 0
	s_lshl_b32 s33, s31, 3
	s_lshl_b64 s[34:35], 1, s33
	s_bcnt1_i32_b64 s16, s[16:17]
	s_mul_i32 s17, s35, s16
	s_mul_i32 s16, s34, s16
	v_mov_b32_e32 v2, s16
	v_mov_b32_e32 v3, s17
	v_mov_b32_e32 v1, 0x3000
	global_atomic_add_x2 v[100:101], v1, v[2:3], s[26:27] offset:1312 sc0
	s_waitcnt vmcnt(0)
	v_lshrrev_b64 v[100:101], s33, v[100:101]
	v_and_b32_e32 v100, 0xff, v100
	v_mov_b32_e32 v101, 0x23fa0
	ds_write_b32 v101, v100
	s_waitcnt lgkmcnt(0)

.LBB0_141:
	s_or_b64 exec, exec, s[0:1]
	v_readlane_b32 s0, v254, 2
	v_readlane_b32 s1, v254, 3
	s_max_i32 s75, s0, 1
	s_cmp_ge_i32 s75, s1
	s_waitcnt lgkmcnt(0)
	s_barrier
	s_cbranch_scc1 .LBB0_738
	v_readlane_b32 s2, v254, 0
	s_lshl_b32 s34, s2, 5
	s_and_b32 s1, s2, 7
	s_cmp_eq_u32 s1, 0
	v_readlane_b32 s3, v254, 1
	s_cselect_b64 s[4:5], -1, 0
	s_mul_i32 s0, s3, s2
	v_writelane_b32 v254, s4, 11
	s_ashr_i32 s1, s2, 3
	s_ashr_i32 s62, s2, 31
	v_writelane_b32 v254, s5, 12
	s_mul_i32 s63, s0, s30
	s_add_u32 s0, s42, 0xc3520
	v_writelane_b32 v254, s1, 13
	s_addc_u32 s1, s43, 0
	v_writelane_b32 v254, s0, 14
	s_mov_b32 s79, 0
	v_mov_b32_e32 v0, 0
	v_writelane_b32 v254, s1, 15
	s_add_u32 s0, s42, 0xc3528
	s_addc_u32 s1, s43, 0
	v_writelane_b32 v254, s0, 16
	v_mov_b32_e32 v235, 0x358637bd
	s_mov_b32 s64, 0xf800000
	v_writelane_b32 v254, s1, 17
	s_add_u32 s0, s42, 0xc0200
	s_addc_u32 s1, s43, 0
	v_writelane_b32 v254, s0, 18
	s_cmp_eq_u32 s31, 15
	s_mov_b32 s66, 0xbfb8aa3b
	v_writelane_b32 v254, s1, 19
	s_cselect_b64 s[0:1], -1, 0
	v_writelane_b32 v254, s0, 20
	s_cmp_eq_u32 s31, 14
	s_mov_b32 s67, 0x1fffe0
	v_writelane_b32 v254, s1, 21
	s_cselect_b64 s[0:1], -1, 0
	v_writelane_b32 v254, s0, 22
	s_cmp_eq_u32 s31, 13
	s_movk_i32 s68, 0xb00
	v_writelane_b32 v254, s1, 23
	s_cselect_b64 s[0:1], -1, 0
	v_writelane_b32 v254, s0, 24
	s_cmp_eq_u32 s31, 12
	s_movk_i32 s69, 0x1600
	v_writelane_b32 v254, s1, 25
	s_cselect_b64 s[0:1], -1, 0
	v_writelane_b32 v254, s0, 26
	s_cmp_eq_u32 s31, 11
	s_movk_i32 s73, 0x161
	v_writelane_b32 v254, s1, 27
	s_cselect_b64 s[0:1], -1, 0
	v_writelane_b32 v254, s0, 28
	s_cmp_eq_u32 s31, 10
	v_mov_b32_e32 v234, 1
	v_writelane_b32 v254, s1, 29
	s_cselect_b64 s[0:1], -1, 0
	v_writelane_b32 v254, s0, 30
	s_cmp_eq_u32 s31, 9
	v_mbcnt_hi_u32_b32 v238, -1, v233
	v_writelane_b32 v254, s1, 31
	s_cselect_b64 s[0:1], -1, 0
	v_writelane_b32 v254, s0, 32
	s_cmp_eq_u32 s31, 8
	v_mov_b32_e32 v239, 0xf149f2ca
	v_writelane_b32 v254, s1, 33
	s_cselect_b64 s[0:1], -1, 0
	v_writelane_b32 v254, s0, 34
	s_cmp_eq_u32 s31, 7
	v_mov_b32_e32 v240, 0x3e38aa3b
	v_writelane_b32 v254, s1, 35
	s_cselect_b64 s[0:1], -1, 0
	v_writelane_b32 v254, s0, 36
	s_cmp_eq_u32 s31, 6
	v_mov_b64_e32 v[252:253], 0x200
	v_writelane_b32 v254, s1, 37
	s_cselect_b64 s[0:1], -1, 0
	v_writelane_b32 v254, s0, 38
	s_cmp_eq_u32 s31, 5
	v_mov_b64_e32 v[236:237], 0x1ff
	v_writelane_b32 v254, s1, 39
	s_cselect_b64 s[0:1], -1, 0
	v_writelane_b32 v254, s0, 40
	s_cmp_eq_u32 s31, 4
	v_mov_b32_e32 v241, 0xf78
	v_writelane_b32 v254, s1, 41
	s_cselect_b64 s[0:1], -1, 0
	v_writelane_b32 v254, s0, 42
	s_cmp_eq_u32 s31, 3
	s_mov_b64 s[90:91], 0x80
	v_writelane_b32 v254, s1, 43
	s_cselect_b64 s[0:1], -1, 0
	v_writelane_b32 v254, s0, 44
	s_cmp_eq_u32 s31, 2
	s_nop 0
	v_writelane_b32 v254, s1, 45
	s_cselect_b64 s[0:1], -1, 0
	v_writelane_b32 v254, s0, 46
	s_cmp_eq_u32 s31, 1
	s_nop 0
	v_writelane_b32 v254, s1, 47
	s_cselect_b64 s[0:1], -1, 0
	v_writelane_b32 v254, s0, 48
	s_cmp_eq_u32 s31, 0
	s_nop 0
	v_writelane_b32 v254, s1, 49
	s_cselect_b64 s[0:1], -1, 0
	v_writelane_b32 v254, s0, 50
	s_nop 1
	v_writelane_b32 v254, s1, 51
	s_lshl_b32 s0, s31, 8
	s_add_u32 s0, s28, s0
	s_addc_u32 s1, s29, 0
	s_add_u32 s4, s0, 0x1400
	s_addc_u32 s5, s1, 0
	v_writelane_b32 v254, s4, 52
	s_add_u32 s0, s0, 0x2400
	s_addc_u32 s1, s1, 0
	v_writelane_b32 v254, s5, 53
	v_writelane_b32 v254, s0, 54
	s_nop 1
	v_writelane_b32 v254, s1, 55
	s_add_u32 s0, s42, 0xc3400
	s_addc_u32 s1, s43, 0
	v_writelane_b32 v254, s0, 56
	s_nop 1
	v_writelane_b32 v254, s1, 57
	s_add_u32 s0, s42, 0xc3500
	s_addc_u32 s1, s43, 0
	v_writelane_b32 v254, s0, 58
	s_ashr_i32 s35, s34, 31
	s_add_i32 s65, 0, 0x4000
	v_writelane_b32 v254, s1, 59
	s_lshl_b64 s[0:1], s[34:35], 12
	v_writelane_b32 v254, s0, 60
	s_add_i32 s74, 0, 0x23f98
	s_nop 0
	v_writelane_b32 v254, s1, 61
	s_lshl_b64 s[0:1], s[34:35], 6
	v_writelane_b32 v254, s0, 62
	s_nop 1
	v_writelane_b32 v254, s1, 63
	s_lshl_b64 s[0:1], s[34:35], 11
	v_writelane_b32 v255, s0, 0
	s_nop 1
	v_writelane_b32 v255, s1, 1
	s_lshl_b32 s0, s2, 7
	v_writelane_b32 v255, s0, 2
	s_lshl_b32 s0, s2, 6
	v_writelane_b32 v255, s0, 3
	s_add_i32 s0, 0, 0x23f90
	v_writelane_b32 v255, s0, 4
	s_add_i32 s0, 0, 0x300
	v_writelane_b32 v255, s0, 5
	s_add_i32 s0, 0, 0x23f88
	v_writelane_b32 v255, s0, 6
	s_add_i32 s0, 0, 0x23f80
	v_writelane_b32 v255, s0, 7
	s_add_i32 s0, 0, 0x23fc0
	v_writelane_b32 v255, s0, 8
	s_add_i32 s0, 0, 0x23fc4
	v_writelane_b32 v255, s0, 9
	v_writelane_b32 v255, s92, 10
	v_writelane_b32 v255, s34, 11
	s_nop 1
	v_writelane_b32 v255, s35, 12
	v_writelane_b32 v255, s62, 13
	v_writelane_b32 v255, s63, 14
	v_writelane_b32 v255, s65, 15
	v_writelane_b32 v255, s74, 16
	v_mov_b32_e32 v100, 0x23fa0
	ds_read_b32 v100, v100
	s_add_u32 s98, s42, 0xc3520
	s_addc_u32 s99, s43, 0
	v_mov_b32_e32 v101, 0
	s_nop 1
	global_load_dwordx4 v[102:105], v101, s[98:99] sc1
	s_waitcnt vmcnt(0) lgkmcnt(0)
	v_readfirstlane_b32 s98, v100
	v_readfirstlane_b32 s99, v102
	v_readfirstlane_b32 s100, v103
	v_readfirstlane_b32 s101, v104
	s_nop 3
	s_xor_b32 s99, s99, 0x20202020
	s_xor_b32 s100, s100, 0x20202020
	s_or_b32 s99, s99, s100
	s_or_b32 s99, s99, s101
	v_readfirstlane_b32 s100, v105
	s_nop 3
	s_or_b32 s99, s99, s100
	s_cmp_lg_u32 s99, 0
	s_cselect_b32 s101, 1, 0
	s_cbranch_scc1 .Lxl_keep
	s_getreg_b32 s99, hwreg(HW_REG_XCC_ID, 0, 4)
	s_lshl_b32 s98, s98, 3
	s_or_b32 s92, s98, s99
.Lxl_keep:
	s_nop 0
	v_writelane_b32 v255, s92, 10
	v_writelane_b32 v255, s101, 60
	s_branch .LBB0_147
